# sliding-window attention P.V section hand-pipelined (reads one tile ahead, two accumulators, cvt_pk staging)
# speedup vs baseline: 1.0067x; 1.0067x over previous
; __device__ void swa_item(const Params& p, int item) {
;     ...
;   bf16x8 qf[4];
;   { long qrow = rowb + (long)(qb * 128 + w * 16 + c) * dil + r;
;     _Pragma("unroll") for (int kk = 0; kk < 4; ++kk) qf[kk] = *(const bf16x8*)(buf + qrow * 4608 + qcol + kk * 32 + q * 8); }
;   __syncthreads();
;   f32x4 S[9];
;   _Pragma("unroll") for (int ci = 0; ci < 9; ++ci) {
;     const int ct = w + ci;
;     f32x4 a = (f32x4){0.f, 0.f, 0.f, 0.f};
;     _Pragma("unroll") for (int kk = 0; kk < 4; ++kk) {
;       bf16x8 kf = *(const bf16x8*)(Ks + (ct * 16 + c) * 136 + kk * 32 + q * 8);
;       a = __builtin_amdgcn_mfma_f32_16x16x32_bf16(qf[kk], kf, a, 0, 0, 0);
;     }
;     S[ci] = a;
;   }
.LBB0_111:
	s_or_b64 exec, exec, s[12:13]
	s_movk_i32 s2, 0x1500
	v_lshlrev_b32_e32 v58, 4, v12
	v_mul_lo_u32 v2, v12, s2
	v_readlane_b32 s12, v254, 10
	v_add_u32_e32 v51, s35, v58
	v_readlane_b32 s26, v254, 13
	v_add_u32_e32 v57, s12, v2
	v_or_b32_e32 v2, v51, v55
	v_ashrrev_i32_e32 v3, 31, v2
	v_lshlrev_b64 v[2:3], s22, v[2:3]
	v_readlane_b32 s27, v254, 14
	v_mov_b64_e32 v[4:5], s[16:17]
	v_and_b32_e32 v52, 48, v50
	v_lshl_add_u64 v[2:3], v[2:3], 0, s[26:27]
	v_mad_u64_u32 v[4:5], s[2:3], v2, s89, v[4:5]
	v_mad_i32_i24 v5, v3, s89, v5
	v_lshl_add_u64 v[2:3], s[0:1], 1, v[4:5]
	v_mov_b32_e32 v53, v1
	v_lshl_add_u64 v[2:3], v[2:3], 0, v[52:53]
	global_load_dwordx4 v[46:49], v[2:3], off
	global_load_dwordx4 v[42:45], v[2:3], off offset:64
	global_load_dwordx4 v[38:41], v[2:3], off offset:128
	global_load_dwordx4 v[34:37], v[2:3], off offset:192
	v_add_u32_e32 v54, s12, v52
	v_or_b32_e32 v53, v58, v55
	s_movk_i32 s3, 0x110
	v_mad_u64_u32 v[30:31], s[0:1], v53, s3, v[54:55]
	s_waitcnt lgkmcnt(0)
	s_barrier
	ds_read_b128 v[2:5], v30
	ds_read_b128 v[6:9], v30 offset:64
	v_bfe_u32 v56, v50, 4, 2
	s_cmp_lg_u32 s34, 0
	s_movk_i32 s2, 0x7f
	v_add_u32_e32 v62, 32, v53
	s_cselect_b64 s[14:15], -1, 0
	s_movk_i32 s18, 0x81
	v_add_u32_e32 v63, 48, v53
	v_add_u32_e32 v61, 16, v53
	v_add_u32_e32 v64, 64, v53
	v_add_u32_e32 v65, 0x50, v53
	v_add_u32_e32 v74, 0x60, v53
	v_add_u32_e32 v75, 0x70, v53
	v_and_b32_e32 v60, 63, v50
	s_waitcnt vmcnt(3) lgkmcnt(1)
	v_mfma_f32_16x16x32_bf16 v[2:5], v[46:49], v[2:5], 0
	ds_read_b128 v[10:13], v30 offset:4416
	ds_read_b128 v[14:17], v30 offset:8768
	ds_read_b128 v[18:21], v30 offset:13120
	s_waitcnt vmcnt(2) lgkmcnt(3)
	v_mfma_f32_16x16x32_bf16 v[2:5], v[42:45], v[6:9], v[2:5]
	ds_read_b128 v[6:9], v30 offset:128
	ds_read_b128 v[22:25], v30 offset:17472
	ds_read_b128 v[26:29], v30 offset:21824
	s_waitcnt vmcnt(1) lgkmcnt(2)
	v_mfma_f32_16x16x32_bf16 v[2:5], v[38:41], v[6:9], v[2:5]
	ds_read_b128 v[6:9], v30 offset:192
	ds_read_b128 v[66:69], v30 offset:26176
	ds_read_b128 v[70:73], v30 offset:30528
	s_waitcnt vmcnt(0) lgkmcnt(2)
	v_mfma_f32_16x16x32_bf16 v[2:5], v[34:37], v[6:9], v[2:5]
	ds_read_b128 v[6:9], v30 offset:4352
	s_waitcnt lgkmcnt(0)
	v_mfma_f32_16x16x32_bf16 v[6:9], v[46:49], v[6:9], 0
	v_mfma_f32_16x16x32_bf16 v[6:9], v[42:45], v[10:13], v[6:9]
	ds_read_b128 v[10:13], v30 offset:4480
	s_waitcnt lgkmcnt(0)
	v_mfma_f32_16x16x32_bf16 v[6:9], v[38:41], v[10:13], v[6:9]
	ds_read_b128 v[10:13], v30 offset:4544
	s_waitcnt lgkmcnt(0)
	v_mfma_f32_16x16x32_bf16 v[6:9], v[34:37], v[10:13], v[6:9]
	ds_read_b128 v[10:13], v30 offset:8704
	s_waitcnt lgkmcnt(0)
	v_mfma_f32_16x16x32_bf16 v[10:13], v[46:49], v[10:13], 0
	v_mfma_f32_16x16x32_bf16 v[10:13], v[42:45], v[14:17], v[10:13]
	ds_read_b128 v[14:17], v30 offset:8832
	s_waitcnt lgkmcnt(0)
	v_mfma_f32_16x16x32_bf16 v[10:13], v[38:41], v[14:17], v[10:13]
	ds_read_b128 v[14:17], v30 offset:8896
	s_waitcnt lgkmcnt(0)
	v_mfma_f32_16x16x32_bf16 v[10:13], v[34:37], v[14:17], v[10:13]
	ds_read_b128 v[14:17], v30 offset:13056
	s_waitcnt lgkmcnt(0)
	v_mfma_f32_16x16x32_bf16 v[14:17], v[46:49], v[14:17], 0
	v_mfma_f32_16x16x32_bf16 v[14:17], v[42:45], v[18:21], v[14:17]
	ds_read_b128 v[18:21], v30 offset:13184
	s_waitcnt lgkmcnt(0)
	v_mfma_f32_16x16x32_bf16 v[14:17], v[38:41], v[18:21], v[14:17]
	ds_read_b128 v[18:21], v30 offset:13248
	s_waitcnt lgkmcnt(0)
	v_mfma_f32_16x16x32_bf16 v[14:17], v[34:37], v[18:21], v[14:17]
	ds_read_b128 v[18:21], v30 offset:17408
	s_waitcnt lgkmcnt(0)
	v_mfma_f32_16x16x32_bf16 v[18:21], v[46:49], v[18:21], 0
	v_mfma_f32_16x16x32_bf16 v[18:21], v[42:45], v[22:25], v[18:21]
	ds_read_b128 v[22:25], v30 offset:17536
	s_waitcnt lgkmcnt(0)
	v_mfma_f32_16x16x32_bf16 v[18:21], v[38:41], v[22:25], v[18:21]
	ds_read_b128 v[22:25], v30 offset:17600
	s_waitcnt lgkmcnt(0)
	v_mfma_f32_16x16x32_bf16 v[18:21], v[34:37], v[22:25], v[18:21]
	ds_read_b128 v[22:25], v30 offset:21760
	s_waitcnt lgkmcnt(0)
	v_mfma_f32_16x16x32_bf16 v[22:25], v[46:49], v[22:25], 0
	v_mfma_f32_16x16x32_bf16 v[22:25], v[42:45], v[26:29], v[22:25]
	ds_read_b128 v[26:29], v30 offset:21888
	s_waitcnt lgkmcnt(0)
	v_mfma_f32_16x16x32_bf16 v[22:25], v[38:41], v[26:29], v[22:25]
	ds_read_b128 v[26:29], v30 offset:21952
	s_waitcnt lgkmcnt(0)
	v_mfma_f32_16x16x32_bf16 v[22:25], v[34:37], v[26:29], v[22:25]
	ds_read_b128 v[26:29], v30 offset:26112
	s_waitcnt lgkmcnt(0)
	v_mfma_f32_16x16x32_bf16 v[26:29], v[46:49], v[26:29], 0
	v_mfma_f32_16x16x32_bf16 v[26:29], v[42:45], v[66:69], v[26:29]
	ds_read_b128 v[66:69], v30 offset:26240
	s_waitcnt lgkmcnt(0)
	v_mfma_f32_16x16x32_bf16 v[26:29], v[38:41], v[66:69], v[26:29]
	ds_read_b128 v[66:69], v30 offset:26304
	s_waitcnt lgkmcnt(0)
	v_mfma_f32_16x16x32_bf16 v[26:29], v[34:37], v[66:69], v[26:29]
	ds_read_b128 v[66:69], v30 offset:30464
	s_waitcnt lgkmcnt(0)
	v_mfma_f32_16x16x32_bf16 v[66:69], v[46:49], v[66:69], 0
	v_mfma_f32_16x16x32_bf16 v[66:69], v[42:45], v[70:73], v[66:69]
	ds_read_b128 v[70:73], v30 offset:30592
	ds_read_b128 v[30:33], v30 offset:30656
	s_waitcnt lgkmcnt(1)
	v_mfma_f32_16x16x32_bf16 v[66:69], v[38:41], v[70:73], v[66:69]
	v_add_u32_e32 v72, 0x80, v58
	v_or_b32_e32 v59, v72, v55
	v_mad_u64_u32 v[70:71], s[0:1], v59, s3, v[54:55]
	s_waitcnt lgkmcnt(0)
	v_mfma_f32_16x16x32_bf16 v[30:33], v[34:37], v[30:33], v[66:69]
	v_cmp_lt_i32_e64 s[0:1], s2, v53
	s_or_b64 s[12:13], s[14:15], s[0:1]
	v_cmp_lt_i32_e64 s[0:1], s2, v62
	ds_read_b128 v[66:69], v70
	s_waitcnt lgkmcnt(0)
	v_mfma_f32_16x16x32_bf16 v[46:49], v[46:49], v[66:69], 0
	ds_read_b128 v[66:69], v70 offset:64
	s_or_b64 s[38:39], s[14:15], s[0:1]
	v_cmp_lt_i32_e64 s[0:1], s2, v63
	s_waitcnt lgkmcnt(0)
; __device__ __forceinline__ float fexp(float x) { return __builtin_amdgcn_exp2f(x * 1.4426950408889634f); }
; #define SHX(v, m) shx_((v), (m), lane)
; __device__ void swa_item(const Params& p, int item) {
;     ...
;   float mx[4], ls[4];
;   _Pragma("unroll") for (int jj = 0; jj < 4; ++jj) {
;     const int qi = w * 16 + q * 4 + jj;
;     float m = -1e30f;
;     _Pragma("unroll") for (int ci = 0; ci < 9; ++ci) {
;       int kj = (w + ci) * 16 + c; int dist = qi + 128 - kj;
;       bool valid = (dist >= 0) && (dist <= 128) && (qb > 0 || kj >= 128);
;       float s = valid ? S[ci][jj] : -1e30f;
;       S[ci][jj] = s; m = fmaxf(m, s);
;     }
;     m = fmaxf(m, SHX(m, 1)); m = fmaxf(m, SHX(m, 2)); m = fmaxf(m, SHX(m, 4)); m = fmaxf(m, SHX(m, 8));
;     float l = 0.f;
;     _Pragma("unroll") for (int ci = 0; ci < 9; ++ci) {
;       float s = S[ci][jj];
;       float pv = (s > -1e29f) ? fexp(s - m) : 0.f;
;       S[ci][jj] = pv; l += pv;
;     }
;     l += SHX(l, 1); l += SHX(l, 2); l += SHX(l, 4); l += SHX(l, 8);
;     mx[jj] = m; ls[jj] = l;
;   }
	v_mfma_f32_16x16x32_bf16 v[42:45], v[42:45], v[66:69], v[46:49]
	v_mov_b32_e32 v66, 0xf149f2ca
	s_nop 1
	ds_read_b128 v[46:49], v70 offset:128
	s_or_b64 s[40:41], s[14:15], s[0:1]
	s_waitcnt lgkmcnt(0)
	v_mfma_f32_16x16x32_bf16 v[38:41], v[38:41], v[46:49], v[42:45]
	s_nop 2
	ds_read_b128 v[42:45], v70 offset:192
	v_cmp_lt_i32_e64 s[0:1], s2, v64
	s_or_b64 s[42:43], s[14:15], s[0:1]
	s_waitcnt lgkmcnt(0)
	v_mfma_f32_16x16x32_bf16 v[34:37], v[34:37], v[42:45], v[38:41]
	v_cmp_lt_i32_e64 s[0:1], s2, v65
	s_nop 1
	v_lshlrev_b32_e32 v38, 2, v56
	v_or_b32_e32 v43, v72, v38
	v_sub_u32_e32 v44, v43, v53
	v_cmp_gt_u32_e32 vcc, s18, v44
	s_and_b64 vcc, vcc, s[12:13]
	v_cndmask_b32_e64 v45, v66, v10, s[38:39]
	v_cndmask_b32_e32 v2, v66, v2, vcc
	v_cmp_lt_i32_e32 vcc, s2, v61
	v_max_f32_e32 v44, v2, v2
	s_or_b64 vcc, s[14:15], vcc
	v_max_f32_e32 v44, 0xf149f2ca, v44
	v_cndmask_b32_e32 v6, v66, v6, vcc
	s_or_b64 s[44:45], s[14:15], s[0:1]
	v_cmp_lt_i32_e64 s[0:1], s2, v74
	v_max3_f32 v10, v44, v6, v45
	v_cndmask_b32_e64 v44, v66, v18, s[42:43]
	s_or_b64 s[46:47], s[14:15], s[0:1]
	v_cmp_lt_i32_e64 s[0:1], s2, v75
	v_sub_u32_e32 v18, v38, v55
	v_cmp_lt_i32_e64 s[50:51], s2, v59
	v_cndmask_b32_e64 v14, v66, v14, s[40:41]
	s_or_b64 s[48:49], s[14:15], s[0:1]
	v_cmp_gt_u32_e64 s[0:1], s18, v18
	s_or_b64 s[14:15], s[14:15], s[50:51]
	v_max3_f32 v10, v10, v14, v44
	v_cndmask_b32_e64 v46, v66, v22, s[44:45]
	v_cndmask_b32_e64 v26, v66, v26, s[46:47]
	s_and_b64 s[0:1], s[0:1], s[14:15]
	v_lshlrev_b32_e32 v39, 2, v60
	v_max3_f32 v10, v10, v46, v26
	v_cndmask_b32_e64 v47, v66, v30, s[48:49]
	v_cndmask_b32_e64 v48, v66, v34, s[0:1]
	v_xor_b32_e32 v42, 4, v39
	v_max3_f32 v10, v10, v47, v48
	ds_bpermute_b32 v18, v42, v10
	v_xor_b32_e32 v41, 8, v39
	v_xor_b32_e32 v40, 16, v39
	v_xor_b32_e32 v39, 32, v39
	s_mov_b32 s2, 0xefa18f08
	s_waitcnt lgkmcnt(0)
	v_max_f32_e32 v18, v18, v18
	v_max_f32_e32 v10, v10, v18
	ds_bpermute_b32 v18, v41, v10
	v_cmp_lt_f32_e64 s[0:1], s2, v2
	v_cndmask_b32_e32 v7, v66, v7, vcc
	v_cndmask_b32_e64 v15, v66, v15, s[40:41]
	v_cndmask_b32_e64 v49, v66, v23, s[44:45]
	s_waitcnt lgkmcnt(0)
	v_max_f32_e32 v18, v18, v18
	v_max_f32_e32 v10, v10, v18
	ds_bpermute_b32 v18, v40, v10
	v_cndmask_b32_e64 v27, v66, v27, s[46:47]
	v_cndmask_b32_e64 v54, v66, v31, s[48:49]
	v_cndmask_b32_e32 v8, v66, v8, vcc
	v_cndmask_b32_e64 v12, v66, v12, s[38:39]
	s_waitcnt lgkmcnt(0)
	v_max_f32_e32 v18, v18, v18
	v_max_f32_e32 v10, v10, v18
	ds_bpermute_b32 v18, v39, v10
	v_cndmask_b32_e64 v60, v66, v32, s[48:49]
	v_cndmask_b32_e64 v16, v66, v16, s[40:41]
	v_cndmask_b32_e64 v20, v66, v20, s[42:43]
	v_cndmask_b32_e64 v28, v66, v28, s[46:47]
	s_waitcnt lgkmcnt(0)
	v_max_f32_e32 v18, v18, v18
	v_max_f32_e32 v22, v10, v18
	v_sub_f32_e32 v2, v2, v22
	v_mul_f32_e32 v2, 0x3fb8aa3b, v2
	v_exp_f32_e32 v2, v2
	v_sub_f32_e32 v34, v46, v22
	v_mul_f32_e32 v34, 0x3fb8aa3b, v34
	v_exp_f32_e32 v34, v34
	v_cndmask_b32_e64 v2, 0, v2, s[0:1]
	v_cmp_lt_f32_e64 s[0:1], s2, v6
	v_sub_f32_e32 v6, v6, v22
	v_mul_f32_e32 v6, 0x3fb8aa3b, v6
	v_exp_f32_e32 v6, v6
	v_add_f32_e32 v18, 0, v2
	v_cndmask_b32_e32 v9, v66, v9, vcc
	v_cndmask_b32_e64 v13, v66, v13, s[38:39]
	v_cndmask_b32_e64 v10, 0, v6, s[0:1]
	v_sub_f32_e32 v6, v45, v22
	v_mul_f32_e32 v6, 0x3fb8aa3b, v6
	v_exp_f32_e32 v6, v6
	v_cmp_lt_f32_e64 s[0:1], s2, v45
	v_add_f32_e32 v18, v10, v18
	v_cndmask_b32_e64 v17, v66, v17, s[40:41]
	v_cndmask_b32_e64 v6, 0, v6, s[0:1]
	v_cmp_lt_f32_e64 s[0:1], s2, v14
	v_sub_f32_e32 v14, v14, v22
	v_mul_f32_e32 v14, 0x3fb8aa3b, v14
	v_exp_f32_e32 v14, v14
	v_add_f32_e32 v30, v6, v18
	v_cndmask_b32_e64 v21, v66, v21, s[42:43]
	v_cndmask_b32_e64 v29, v66, v29, s[46:47]
	v_cndmask_b32_e64 v18, 0, v14, s[0:1]
	v_sub_f32_e32 v14, v44, v22
	v_mul_f32_e32 v14, 0x3fb8aa3b, v14
	v_exp_f32_e32 v14, v14
	v_cmp_lt_f32_e64 s[0:1], s2, v44
	v_add_f32_e32 v30, v18, v30
	v_cndmask_b32_e64 v33, v66, v33, s[48:49]
	v_cndmask_b32_e64 v14, 0, v14, s[0:1]
	v_cmp_lt_f32_e64 s[0:1], s2, v46
	v_add_f32_e32 v30, v14, v30
	s_nop 0
	v_cndmask_b32_e64 v34, 0, v34, s[0:1]
	v_cmp_lt_f32_e64 s[0:1], s2, v26
	v_sub_f32_e32 v26, v26, v22
	v_mul_f32_e32 v26, 0x3fb8aa3b, v26
	v_exp_f32_e32 v26, v26
	v_add_f32_e32 v44, v34, v30
	s_barrier
	v_cndmask_b32_e64 v30, 0, v26, s[0:1]
	v_add_f32_e32 v26, v30, v44
	v_sub_f32_e32 v44, v47, v22
	v_mul_f32_e32 v44, 0x3fb8aa3b, v44
	v_exp_f32_e32 v44, v44
	v_cmp_lt_f32_e64 s[0:1], s2, v47
	s_nop 1
	v_cndmask_b32_e64 v45, 0, v44, s[0:1]
	v_sub_f32_e32 v44, v48, v22
	v_mul_f32_e32 v44, 0x3fb8aa3b, v44
	v_exp_f32_e32 v44, v44
	v_cmp_lt_f32_e64 s[0:1], s2, v48
	v_add_f32_e32 v26, v45, v26
	v_cndmask_b32_e64 v48, v66, v11, s[38:39]
	v_cndmask_b32_e64 v44, 0, v44, s[0:1]
	v_add_f32_e32 v26, v44, v26
	ds_bpermute_b32 v46, v42, v26
	s_waitcnt lgkmcnt(0)
	v_add_f32_e32 v26, v26, v46
	ds_bpermute_b32 v46, v41, v26
	s_waitcnt lgkmcnt(0)
	v_add_f32_e32 v26, v26, v46
	ds_bpermute_b32 v46, v40, v26
	s_waitcnt lgkmcnt(0)
	v_add_f32_e32 v26, v26, v46
	ds_bpermute_b32 v46, v39, v26
	s_waitcnt lgkmcnt(0)
	v_add_f32_e32 v26, v26, v46
	v_or_b32_e32 v46, 1, v43
	v_sub_u32_e32 v47, v46, v53
	v_cmp_gt_u32_e64 s[0:1], s18, v47
	s_and_b64 s[0:1], s[0:1], s[12:13]
	s_nop 0
	v_cndmask_b32_e64 v3, v66, v3, s[0:1]
	v_max_f32_e32 v47, v3, v3
	v_max_f32_e32 v47, 0xf149f2ca, v47
	v_max3_f32 v11, v47, v7, v48
	v_cndmask_b32_e64 v47, v66, v19, s[42:43]
	v_sub_u32_e32 v19, v46, v59
	v_cmp_gt_u32_e64 s[0:1], s18, v19
	v_max3_f32 v11, v11, v15, v47
	s_and_b64 s[0:1], s[0:1], s[14:15]
	v_max3_f32 v11, v11, v49, v27
	v_cndmask_b32_e64 v35, v66, v35, s[0:1]
	v_max3_f32 v11, v11, v54, v35
	ds_bpermute_b32 v19, v42, v11
	v_cmp_lt_f32_e64 s[0:1], s2, v3
	s_waitcnt lgkmcnt(0)
; __device__ __forceinline__ float fexp(float x) { return __builtin_amdgcn_exp2f(x * 1.4426950408889634f); }
; #define SHX(v, m) shx_((v), (m), lane)
; __device__ void swa_item(const Params& p, int item) {
;     ...
;   _Pragma("unroll") for (int jj = 0; jj < 4; ++jj) {
;     const int qi = w * 16 + q * 4 + jj;
;     float m = -1e30f;
;     _Pragma("unroll") for (int ci = 0; ci < 9; ++ci) {
;       int kj = (w + ci) * 16 + c; int dist = qi + 128 - kj;
;       bool valid = (dist >= 0) && (dist <= 128) && (qb > 0 || kj >= 128);
;       float s = valid ? S[ci][jj] : -1e30f;
;       S[ci][jj] = s; m = fmaxf(m, s);
;     }
;     m = fmaxf(m, SHX(m, 1)); m = fmaxf(m, SHX(m, 2)); m = fmaxf(m, SHX(m, 4)); m = fmaxf(m, SHX(m, 8));
;     float l = 0.f;
;     _Pragma("unroll") for (int ci = 0; ci < 9; ++ci) {
;       float s = S[ci][jj];
;       float pv = (s > -1e29f) ? fexp(s - m) : 0.f;
;       S[ci][jj] = pv; l += pv;
;     }
;     l += SHX(l, 1); l += SHX(l, 2); l += SHX(l, 4); l += SHX(l, 8);
;     mx[jj] = m; ls[jj] = l;
;   }
	v_max_f32_e32 v19, v19, v19
	v_max_f32_e32 v11, v11, v19
	ds_bpermute_b32 v19, v41, v11
	s_waitcnt lgkmcnt(0)
	v_max_f32_e32 v19, v19, v19
	v_max_f32_e32 v11, v11, v19
	ds_bpermute_b32 v19, v40, v11
	s_waitcnt lgkmcnt(0)
	v_max_f32_e32 v19, v19, v19
	v_max_f32_e32 v11, v11, v19
	ds_bpermute_b32 v19, v39, v11
	s_waitcnt lgkmcnt(0)
	v_max_f32_e32 v19, v19, v19
	v_max_f32_e32 v23, v11, v19
	v_sub_f32_e32 v3, v3, v23
	v_mul_f32_e32 v3, 0x3fb8aa3b, v3
	v_exp_f32_e32 v3, v3
	v_sub_f32_e32 v46, v49, v23
	v_mul_f32_e32 v46, 0x3fb8aa3b, v46
	v_exp_f32_e32 v46, v46
	v_cndmask_b32_e64 v3, 0, v3, s[0:1]
	v_cmp_lt_f32_e64 s[0:1], s2, v7
	v_sub_f32_e32 v7, v7, v23
	v_mul_f32_e32 v7, 0x3fb8aa3b, v7
	v_exp_f32_e32 v7, v7
	v_add_f32_e32 v19, 0, v3
	v_cndmask_b32_e64 v11, 0, v7, s[0:1]
	v_sub_f32_e32 v7, v48, v23
	v_mul_f32_e32 v7, 0x3fb8aa3b, v7
	v_exp_f32_e32 v7, v7
	v_cmp_lt_f32_e64 s[0:1], s2, v48
	v_add_f32_e32 v19, v11, v19
	s_nop 0
	v_cndmask_b32_e64 v7, 0, v7, s[0:1]
	v_cmp_lt_f32_e64 s[0:1], s2, v15
	v_sub_f32_e32 v15, v15, v23
	v_mul_f32_e32 v15, 0x3fb8aa3b, v15
	v_exp_f32_e32 v15, v15
	v_add_f32_e32 v31, v7, v19
	v_cndmask_b32_e64 v19, 0, v15, s[0:1]
	v_sub_f32_e32 v15, v47, v23
	v_mul_f32_e32 v15, 0x3fb8aa3b, v15
	v_exp_f32_e32 v15, v15
	v_cmp_lt_f32_e64 s[0:1], s2, v47
	v_add_f32_e32 v31, v19, v31
	s_nop 0
	v_cndmask_b32_e64 v15, 0, v15, s[0:1]
	v_cmp_lt_f32_e64 s[0:1], s2, v49
	v_add_f32_e32 v31, v15, v31
	s_nop 0
	v_cndmask_b32_e64 v46, 0, v46, s[0:1]
	v_cmp_lt_f32_e64 s[0:1], s2, v27
	v_sub_f32_e32 v27, v27, v23
	v_mul_f32_e32 v27, 0x3fb8aa3b, v27
	v_exp_f32_e32 v27, v27
	v_add_f32_e32 v47, v46, v31
	v_cndmask_b32_e64 v31, 0, v27, s[0:1]
	v_add_f32_e32 v27, v31, v47
	v_sub_f32_e32 v47, v54, v23
	v_mul_f32_e32 v47, 0x3fb8aa3b, v47
	v_exp_f32_e32 v47, v47
	v_cmp_lt_f32_e64 s[0:1], s2, v54
	v_cndmask_b32_e64 v54, v66, v24, s[44:45]
	s_nop 0
	v_cndmask_b32_e64 v47, 0, v47, s[0:1]
	v_cmp_lt_f32_e64 s[0:1], s2, v35
	v_sub_f32_e32 v35, v35, v23
	v_mul_f32_e32 v35, 0x3fb8aa3b, v35
	v_exp_f32_e32 v35, v35
	v_add_f32_e32 v27, v47, v27
	v_cndmask_b32_e64 v35, 0, v35, s[0:1]
	v_add_f32_e32 v27, v35, v27
	ds_bpermute_b32 v48, v42, v27
	s_waitcnt lgkmcnt(0)
	v_add_f32_e32 v27, v27, v48
	ds_bpermute_b32 v48, v41, v27
	s_waitcnt lgkmcnt(0)
	v_add_f32_e32 v27, v27, v48
	ds_bpermute_b32 v48, v40, v27
	s_waitcnt lgkmcnt(0)
	v_add_f32_e32 v27, v27, v48
	ds_bpermute_b32 v48, v39, v27
	s_waitcnt lgkmcnt(0)
	v_add_f32_e32 v27, v27, v48
	v_or_b32_e32 v48, 2, v43
	v_sub_u32_e32 v49, v48, v53
	v_cmp_gt_u32_e64 s[0:1], s18, v49
	s_and_b64 s[0:1], s[0:1], s[12:13]
	v_sub_u32_e32 v32, v48, v59
	v_cndmask_b32_e64 v4, v66, v4, s[0:1]
	v_max_f32_e32 v49, v4, v4
	v_max_f32_e32 v49, 0xf149f2ca, v49
	v_max3_f32 v49, v49, v8, v12
	v_cmp_gt_u32_e64 s[0:1], s18, v32
	v_max3_f32 v49, v49, v16, v20
	s_and_b64 s[0:1], s[0:1], s[14:15]
	v_max3_f32 v24, v49, v54, v28
	v_cndmask_b32_e64 v61, v66, v36, s[0:1]
	v_max3_f32 v24, v24, v60, v61
	ds_bpermute_b32 v32, v42, v24
	v_cmp_lt_f32_e64 s[0:1], s2, v4
	v_or_b32_e32 v43, 3, v43
	v_sub_u32_e32 v53, v43, v53
	v_sub_u32_e32 v43, v43, v59
	s_waitcnt lgkmcnt(0)
	v_max_f32_e32 v32, v32, v32
	v_max_f32_e32 v24, v24, v32
	ds_bpermute_b32 v32, v41, v24
	v_cmp_gt_u32_e32 vcc, s18, v43
	s_and_b64 vcc, vcc, s[14:15]
	s_waitcnt lgkmcnt(0)
	v_max_f32_e32 v32, v32, v32
	v_max_f32_e32 v24, v24, v32
	ds_bpermute_b32 v32, v40, v24
	v_cndmask_b32_e32 v37, v66, v37, vcc
	s_waitcnt lgkmcnt(0)
	v_max_f32_e32 v32, v32, v32
	v_max_f32_e32 v24, v24, v32
	ds_bpermute_b32 v32, v39, v24
	s_waitcnt lgkmcnt(0)
	v_max_f32_e32 v32, v32, v32
	v_max_f32_e32 v24, v24, v32
	v_sub_f32_e32 v4, v4, v24
	v_mul_f32_e32 v4, 0x3fb8aa3b, v4
	v_exp_f32_e32 v4, v4
	s_nop 0
	v_cndmask_b32_e64 v4, 0, v4, s[0:1]
	v_cmp_lt_f32_e64 s[0:1], s2, v8
	v_sub_f32_e32 v8, v8, v24
	v_mul_f32_e32 v8, 0x3fb8aa3b, v8
	v_exp_f32_e32 v8, v8
	v_add_f32_e32 v32, 0, v4
	v_cndmask_b32_e64 v8, 0, v8, s[0:1]
	v_cmp_lt_f32_e64 s[0:1], s2, v12
	v_sub_f32_e32 v12, v12, v24
	v_mul_f32_e32 v12, 0x3fb8aa3b, v12
	v_exp_f32_e32 v12, v12
	v_add_f32_e32 v32, v8, v32
	v_cndmask_b32_e64 v12, 0, v12, s[0:1]
	v_cmp_lt_f32_e64 s[0:1], s2, v16
	v_sub_f32_e32 v16, v16, v24
	v_mul_f32_e32 v16, 0x3fb8aa3b, v16
	v_exp_f32_e32 v16, v16
	v_add_f32_e32 v32, v12, v32
	v_cndmask_b32_e64 v16, 0, v16, s[0:1]
	v_cmp_lt_f32_e64 s[0:1], s2, v20
	v_sub_f32_e32 v20, v20, v24
	v_mul_f32_e32 v20, 0x3fb8aa3b, v20
	v_exp_f32_e32 v20, v20
	v_add_f32_e32 v36, v16, v32
	v_cndmask_b32_e64 v32, 0, v20, s[0:1]
	v_add_f32_e32 v20, v32, v36
	v_sub_f32_e32 v36, v54, v24
	v_mul_f32_e32 v36, 0x3fb8aa3b, v36
	v_exp_f32_e32 v36, v36
	v_cmp_lt_f32_e64 s[0:1], s2, v54
	s_nop 1
	v_cndmask_b32_e64 v49, 0, v36, s[0:1]
	v_cmp_lt_f32_e64 s[0:1], s2, v28
	v_sub_f32_e32 v28, v28, v24
	v_mul_f32_e32 v28, 0x3fb8aa3b, v28
	v_exp_f32_e32 v28, v28
	v_add_f32_e32 v20, v49, v20
	v_cndmask_b32_e64 v48, 0, v28, s[0:1]
	v_sub_f32_e32 v28, v60, v24
	v_mul_f32_e32 v28, 0x3fb8aa3b, v28
	v_exp_f32_e32 v28, v28
	v_cmp_lt_f32_e64 s[0:1], s2, v60
	v_add_f32_e32 v20, v48, v20
	s_nop 0
	v_cndmask_b32_e64 v36, 0, v28, s[0:1]
	v_add_f32_e32 v28, v36, v20
	v_sub_f32_e32 v20, v61, v24
	v_mul_f32_e32 v20, 0x3fb8aa3b, v20
	v_exp_f32_e32 v20, v20
	v_cmp_lt_f32_e64 s[0:1], s2, v61
	s_nop 1
	v_cndmask_b32_e64 v20, 0, v20, s[0:1]
	v_add_f32_e32 v28, v20, v28
	ds_bpermute_b32 v54, v42, v28
	v_cmp_gt_u32_e64 s[0:1], s18, v53
	s_and_b64 s[0:1], s[0:1], s[12:13]
	s_waitcnt lgkmcnt(0)
	v_add_f32_e32 v28, v28, v54
	ds_bpermute_b32 v54, v41, v28
	v_cndmask_b32_e64 v5, v66, v5, s[0:1]
	v_max_f32_e32 v53, v5, v5
	v_max_f32_e32 v53, 0xf149f2ca, v53
	v_max3_f32 v53, v53, v9, v13
	s_waitcnt lgkmcnt(0)
; __device__ __forceinline__ float fexp(float x) { return __builtin_amdgcn_exp2f(x * 1.4426950408889634f); }
; #define SHX(v, m) shx_((v), (m), lane)
; __device__ void swa_item(const Params& p, int item) {
;     ...
;   _Pragma("unroll") for (int jj = 0; jj < 4; ++jj) {
;     const int qi = w * 16 + q * 4 + jj;
;     float m = -1e30f;
;     _Pragma("unroll") for (int ci = 0; ci < 9; ++ci) {
;       int kj = (w + ci) * 16 + c; int dist = qi + 128 - kj;
;       bool valid = (dist >= 0) && (dist <= 128) && (qb > 0 || kj >= 128);
;       float s = valid ? S[ci][jj] : -1e30f;
;       S[ci][jj] = s; m = fmaxf(m, s);
;     }
;     m = fmaxf(m, SHX(m, 1)); m = fmaxf(m, SHX(m, 2)); m = fmaxf(m, SHX(m, 4)); m = fmaxf(m, SHX(m, 8));
;     float l = 0.f;
;     _Pragma("unroll") for (int ci = 0; ci < 9; ++ci) {
;       float s = S[ci][jj];
;       float pv = (s > -1e29f) ? fexp(s - m) : 0.f;
;       S[ci][jj] = pv; l += pv;
;     }
;     l += SHX(l, 1); l += SHX(l, 2); l += SHX(l, 4); l += SHX(l, 8);
;     mx[jj] = m; ls[jj] = l;
;   }
;   __syncthreads();
;   _Pragma("unroll") for (int ci = 0; ci < 9; ++ci) _Pragma("unroll") for (int jj = 0; jj < 4; ++jj) Pl[(q * 4 + jj) * 168 + ci * 16 + c] = f2bf(S[ci][jj]);
;   _Pragma("unroll") for (int jj = 0; jj < 4; ++jj) Pl[(q * 4 + jj) * 168 + 144 + c] = 0;
	v_add_f32_e32 v28, v28, v54
	ds_bpermute_b32 v54, v40, v28
	v_max3_f32 v53, v53, v17, v21
	v_cmp_lt_f32_e32 vcc, s2, v5
	s_movk_i32 s0, 0x540
	s_waitcnt lgkmcnt(0)
	v_add_f32_e32 v28, v28, v54
	ds_bpermute_b32 v54, v39, v28
	s_waitcnt lgkmcnt(0)
	v_add_f32_e32 v28, v28, v54
	v_cndmask_b32_e64 v54, v66, v25, s[44:45]
	v_max3_f32 v25, v53, v54, v29
	v_max3_f32 v25, v25, v33, v37
	ds_bpermute_b32 v43, v42, v25
	s_waitcnt lgkmcnt(0)
	v_max_f32_e32 v43, v43, v43
	v_max_f32_e32 v25, v25, v43
	ds_bpermute_b32 v43, v41, v25
	s_waitcnt lgkmcnt(0)
	v_max_f32_e32 v43, v43, v43
	v_max_f32_e32 v25, v25, v43
	ds_bpermute_b32 v43, v40, v25
	s_waitcnt lgkmcnt(0)
	v_max_f32_e32 v43, v43, v43
	v_max_f32_e32 v25, v25, v43
	ds_bpermute_b32 v43, v39, v25
	s_waitcnt lgkmcnt(0)
	v_max_f32_e32 v43, v43, v43
	v_max_f32_e32 v25, v25, v43
	v_sub_f32_e32 v5, v5, v25
	v_mul_f32_e32 v5, 0x3fb8aa3b, v5
	v_exp_f32_e32 v5, v5
	v_sub_f32_e32 v53, v54, v25
	v_mul_f32_e32 v53, 0x3fb8aa3b, v53
	v_exp_f32_e32 v53, v53
	v_cndmask_b32_e32 v5, 0, v5, vcc
	v_cmp_lt_f32_e32 vcc, s2, v9
	v_sub_f32_e32 v9, v9, v25
	v_mul_f32_e32 v9, 0x3fb8aa3b, v9
	v_exp_f32_e32 v9, v9
	v_add_f32_e32 v43, 0, v5
	v_cndmask_b32_e32 v9, 0, v9, vcc
	v_cmp_lt_f32_e32 vcc, s2, v13
	v_sub_f32_e32 v13, v13, v25
	v_mul_f32_e32 v13, 0x3fb8aa3b, v13
	v_exp_f32_e32 v13, v13
	v_add_f32_e32 v43, v9, v43
	v_cndmask_b32_e32 v13, 0, v13, vcc
	v_cmp_lt_f32_e32 vcc, s2, v17
	v_sub_f32_e32 v17, v17, v25
	v_mul_f32_e32 v17, 0x3fb8aa3b, v17
	v_exp_f32_e32 v17, v17
	v_add_f32_e32 v43, v13, v43
	v_cndmask_b32_e32 v17, 0, v17, vcc
	v_cmp_lt_f32_e32 vcc, s2, v21
	v_sub_f32_e32 v21, v21, v25
	v_mul_f32_e32 v21, 0x3fb8aa3b, v21
	v_exp_f32_e32 v21, v21
	v_add_f32_e32 v43, v17, v43
	v_cndmask_b32_e32 v21, 0, v21, vcc
	v_cmp_lt_f32_e32 vcc, s2, v54
	v_add_f32_e32 v43, v21, v43
	s_nop 0
	v_cndmask_b32_e32 v53, 0, v53, vcc
	v_cmp_lt_f32_e32 vcc, s2, v29
	v_sub_f32_e32 v29, v29, v25
	v_mul_f32_e32 v29, 0x3fb8aa3b, v29
	v_exp_f32_e32 v29, v29
	v_add_f32_e32 v43, v53, v43
	v_cndmask_b32_e32 v54, 0, v29, vcc
	v_cmp_lt_f32_e32 vcc, s2, v33
	v_sub_f32_e32 v33, v33, v25
	v_mul_f32_e32 v33, 0x3fb8aa3b, v33
	v_exp_f32_e32 v33, v33
	v_add_f32_e32 v29, v54, v43
	v_or_b32_e32 v43, 1, v38
	v_cndmask_b32_e32 v33, 0, v33, vcc
	v_cmp_lt_f32_e32 vcc, s2, v37
	v_sub_f32_e32 v37, v37, v25
	v_mul_f32_e32 v37, 0x3fb8aa3b, v37
	v_exp_f32_e32 v37, v37
	v_add_f32_e32 v29, v33, v29
	s_movk_i32 s2, 0xc0
	v_cndmask_b32_e32 v37, 0, v37, vcc
	v_add_f32_e32 v29, v37, v29
	ds_bpermute_b32 v42, v42, v29
	s_waitcnt lgkmcnt(0)
	v_add_f32_e32 v29, v29, v42
	ds_bpermute_b32 v41, v41, v29
	s_waitcnt lgkmcnt(0)
	v_add_f32_e32 v29, v29, v41
	ds_bpermute_b32 v40, v40, v29
	v_bfe_u32 v41, v2, 16, 1
	v_add3_u32 v2, v2, v41, s72
	v_mul_u32_u24_e32 v41, 0x540, v56
	s_waitcnt lgkmcnt(0)
	v_add_f32_e32 v29, v29, v40
	ds_bpermute_b32 v39, v39, v29
	s_waitcnt lgkmcnt(0)
	v_add_f32_e32 v29, v29, v39
	v_lshlrev_b32_e32 v39, 1, v55
	v_add_u32_e32 v40, v57, v39
	v_mad_u32_u24 v42, v56, s0, v40
	ds_write_b16_d16_hi v42, v2
	v_bfe_u32 v2, v3, 16, 1
	s_movk_i32 s0, 0x150
	v_add3_u32 v2, v3, v2, s72
	v_mad_u32_u24 v59, v43, s0, v40
	ds_write_b16_d16_hi v59, v2
	v_bfe_u32 v2, v4, 16, 1
	v_add3_u32 v2, v4, v2, s72
	v_mad_u32_u24 v4, v43, s0, s0
	v_add_u32_e32 v60, v40, v4
	ds_write_b16_d16_hi v60, v2
	v_bfe_u32 v2, v5, 16, 1
	v_add3_u32 v2, v5, v2, s72
	v_mov_b32_e32 v5, 0x2a0
	v_mad_u32_u24 v5, v43, s0, v5
	v_add_u32_e32 v61, v40, v5
	ds_write_b16_d16_hi v61, v2
	v_bfe_u32 v2, v10, 16, 1
	v_add3_u32 v2, v10, v2, s72
	ds_write_b16_d16_hi v42, v2 offset:32
	v_bfe_u32 v2, v11, 16, 1
	v_add3_u32 v2, v11, v2, s72
	ds_write_b16_d16_hi v59, v2 offset:32
	v_bfe_u32 v2, v8, 16, 1
	v_add3_u32 v2, v8, v2, s72
	ds_write_b16_d16_hi v60, v2 offset:32
	v_bfe_u32 v2, v9, 16, 1
	v_add3_u32 v2, v9, v2, s72
	ds_write_b16_d16_hi v61, v2 offset:32
	v_bfe_u32 v2, v6, 16, 1
	v_add3_u32 v2, v6, v2, s72
	ds_write_b16_d16_hi v42, v2 offset:64
	v_bfe_u32 v2, v7, 16, 1
	v_add3_u32 v2, v7, v2, s72
	ds_write_b16_d16_hi v59, v2 offset:64
	v_bfe_u32 v2, v12, 16, 1
	v_add3_u32 v2, v12, v2, s72
	ds_write_b16_d16_hi v60, v2 offset:64
	v_bfe_u32 v2, v13, 16, 1
	v_add3_u32 v2, v13, v2, s72
	ds_write_b16_d16_hi v61, v2 offset:64
	v_bfe_u32 v2, v18, 16, 1
	v_add3_u32 v2, v18, v2, s72
	ds_write_b16_d16_hi v42, v2 offset:96
	v_bfe_u32 v2, v19, 16, 1
	v_add3_u32 v2, v19, v2, s72
	ds_write_b16_d16_hi v59, v2 offset:96
	v_bfe_u32 v2, v16, 16, 1
	v_add3_u32 v2, v16, v2, s72
	ds_write_b16_d16_hi v60, v2 offset:96
	v_bfe_u32 v2, v17, 16, 1
	v_add3_u32 v2, v17, v2, s72
	ds_write_b16_d16_hi v61, v2 offset:96
	v_bfe_u32 v2, v14, 16, 1
	v_add3_u32 v2, v14, v2, s72
	ds_write_b16_d16_hi v42, v2 offset:128
	v_bfe_u32 v2, v15, 16, 1
	v_add3_u32 v2, v15, v2, s72
	ds_write_b16_d16_hi v59, v2 offset:128
	v_bfe_u32 v2, v32, 16, 1
	v_add3_u32 v2, v32, v2, s72
	ds_write_b16_d16_hi v60, v2 offset:128
	v_bfe_u32 v2, v21, 16, 1
	v_add3_u32 v2, v21, v2, s72
	ds_write_b16_d16_hi v61, v2 offset:128
	v_bfe_u32 v2, v34, 16, 1
	v_add3_u32 v2, v34, v2, s72
	ds_write_b16_d16_hi v42, v2 offset:160
	v_bfe_u32 v2, v46, 16, 1
	v_add3_u32 v2, v46, v2, s72
	ds_write_b16_d16_hi v59, v2 offset:160
	v_bfe_u32 v2, v49, 16, 1
	v_add3_u32 v2, v49, v2, s72
	ds_write_b16_d16_hi v60, v2 offset:160
	v_bfe_u32 v2, v53, 16, 1
	v_add3_u32 v2, v53, v2, s72
	ds_write_b16_d16_hi v61, v2 offset:160
	v_bfe_u32 v2, v30, 16, 1
	v_add3_u32 v2, v30, v2, s72
	ds_write_b16_d16_hi v42, v2 offset:192
	v_bfe_u32 v2, v31, 16, 1
	v_add3_u32 v2, v31, v2, s72
	ds_write_b16_d16_hi v59, v2 offset:192
	v_bfe_u32 v2, v48, 16, 1
	v_add3_u32 v2, v48, v2, s72
	ds_write_b16_d16_hi v60, v2 offset:192
	v_bfe_u32 v2, v54, 16, 1
	v_add3_u32 v2, v54, v2, s72
	ds_write_b16_d16_hi v61, v2 offset:192
	v_bfe_u32 v2, v45, 16, 1
	v_add3_u32 v2, v45, v2, s72
	ds_write_b16_d16_hi v42, v2 offset:224
	v_bfe_u32 v2, v47, 16, 1
	v_add3_u32 v2, v47, v2, s72
	ds_write_b16_d16_hi v59, v2 offset:224
	v_bfe_u32 v2, v36, 16, 1
	v_add3_u32 v2, v36, v2, s72
	ds_write_b16_d16_hi v60, v2 offset:224
	v_bfe_u32 v2, v33, 16, 1
	v_add3_u32 v2, v33, v2, s72
	ds_write_b16_d16_hi v61, v2 offset:224
	v_bfe_u32 v2, v44, 16, 1
	v_add3_u32 v2, v44, v2, s72
	ds_write_b16_d16_hi v42, v2 offset:256
	v_bfe_u32 v2, v35, 16, 1
	v_add3_u32 v2, v35, v2, s72
	ds_write_b16_d16_hi v59, v2 offset:256
	v_bfe_u32 v2, v20, 16, 1
	v_add3_u32 v2, v20, v2, s72
	ds_write_b16_d16_hi v60, v2 offset:256
	v_bfe_u32 v2, v37, 16, 1
	v_add3_u32 v2, v37, v2, s72
	v_mul_u32_u24_e32 v3, 0x150, v43
	ds_write_b16_d16_hi v61, v2 offset:256
	v_add3_u32 v2, v57, v41, v39
	ds_write_b16 v2, v1 offset:288
	v_add3_u32 v2, v57, v3, v39
	ds_write_b16 v2, v1 offset:288
	v_add3_u32 v2, v57, v4, v39
	v_lshl_add_u32 v45, v56, 3, v58
	s_movk_i32 s0, 0x100
	ds_write_b16 v2, v1 offset:288
	v_add3_u32 v2, v57, v5, v39
	v_and_b32_e32 v46, 8, v50
	v_cmp_gt_i32_e32 vcc, s0, v45
	ds_write_b16 v2, v1 offset:288
	v_mul_u32_u24_e32 v2, 0x150, v55
	v_cndmask_b32_e32 v30, 0, v46, vcc
	s_waitcnt lgkmcnt(0)
; __device__ __forceinline__ float frcp(float x) { return __builtin_amdgcn_rcpf(x); }
; __device__ void swa_item(const Params& p, int item) {
;     ...
;   float il[4];
;   _Pragma("unroll") for (int jj = 0; jj < 4; ++jj) il[jj] = frcp(ls[jj]);
;   bfu* Ow = Pl;
;   _Pragma("unroll") for (int dt = 0; dt < 8; ++dt) {
;     f32x4 a = (f32x4){0.f, 0.f, 0.f, 0.f};
;     _Pragma("unroll") for (int kk = 0; kk < 5; ++kk) {
;       const int k0_ = w * 16 + kk * 32 + q * 8; const int ch_ = k0_ >> 3;
;       const int chp_ = (ch_ < 32) ? (ch_ ^ (((dt * 16 + c) >> 3) & 15)) : ch_;
;       bf16x8 vf = *(const bf16x8*)(Vt + (dt * 16 + c) * 280 + chp_ * 8);
;       a = __builtin_amdgcn_mfma_f32_16x16x32_bf16(pf[kk], vf, a, 0, 0, 0);
;     }
;     _Pragma("unroll") for (int jj = 0; jj < 4; ++jj) Ow[(q * 4 + jj) * 136 + dt * 16 + c] = f2bf(a[jj] * il[jj]);
;   }
	v_add3_u32 v2, v57, v2, v52
	v_mad_u32_u24 v47, v55, s25, 0
	v_xor_b32_e32 v30, v30, v45
	ds_read_b128 v[18:21], v2
	ds_read_b128 v[14:17], v2 offset:64
	ds_read_b128 v[10:13], v2 offset:128
	ds_read_b128 v[6:9], v2 offset:192
	ds_read_b128 v[2:5], v2 offset:256
	s_waitcnt lgkmcnt(0)
	s_movk_i32 s0, 0xe0
	v_cmp_gt_i32_e64 s[0:1], s0, v45
	v_cmp_gt_i32_e64 s[38:39], s2, v45
	s_movk_i32 s2, 0xa0
	v_cmp_gt_i32_e64 s[40:41], s2, v45
	s_movk_i32 s2, 0x80
	v_cmp_gt_i32_e64 s[42:43], s2, v45
	v_add_u32_e32 v48, 32, v45
	v_add_u32_e32 v49, 64, v45
	v_add_u32_e32 v50, 0x60, v45
	v_add_u32_e32 v52, 0x80, v45
	v_rcp_f32_e32 v39, v26
	v_rcp_f32_e32 v41, v27
	v_rcp_f32_e32 v42, v28
	v_rcp_f32_e32 v44, v29
	s_movk_i32 s2, 0x440
	v_mad_u32_u24 v53, v56, s2, v40
	v_mad_u32_u24 v40, v43, s3, v40
	v_cndmask_b32_e32 v116, 0, v46, vcc
	v_xor_b32_e32 v116, v116, v45
	v_lshl_add_u32 v116, v116, 1, v47
	v_cndmask_b32_e64 v117, 0, v46, s[0:1]
	v_xor_b32_e32 v117, v117, v48
	v_lshl_add_u32 v117, v117, 1, v47
	v_cndmask_b32_e64 v118, 0, v46, s[38:39]
	v_xor_b32_e32 v118, v118, v49
	v_lshl_add_u32 v118, v118, 1, v47
	v_cndmask_b32_e64 v119, 0, v46, s[40:41]
	v_xor_b32_e32 v119, v119, v50
	v_lshl_add_u32 v119, v119, 1, v47
	v_cndmask_b32_e64 v120, 0, v46, s[42:43]
	v_xor_b32_e32 v120, v120, v52
	v_lshl_add_u32 v120, v120, 1, v47
	ds_read_b128 v[76:79], v116
	ds_read_b128 v[80:83], v117
	ds_read_b128 v[84:87], v118
	ds_read_b128 v[88:91], v119
	ds_read_b128 v[92:95], v120
	v_or_b32_e32 v121, 16, v46
	v_cndmask_b32_e32 v116, 0, v121, vcc
	v_xor_b32_e32 v116, v116, v45
	v_lshl_add_u32 v116, v116, 1, v47
	v_cndmask_b32_e64 v117, 0, v121, s[0:1]
	v_xor_b32_e32 v117, v117, v48
	v_lshl_add_u32 v117, v117, 1, v47
	v_cndmask_b32_e64 v118, 0, v121, s[38:39]
	v_xor_b32_e32 v118, v118, v49
	v_lshl_add_u32 v118, v118, 1, v47
	v_cndmask_b32_e64 v119, 0, v121, s[40:41]
	v_xor_b32_e32 v119, v119, v50
	v_lshl_add_u32 v119, v119, 1, v47
	v_cndmask_b32_e64 v120, 0, v121, s[42:43]
	v_xor_b32_e32 v120, v120, v52
	v_lshl_add_u32 v120, v120, 1, v47
	ds_read_b128 v[96:99], v116 offset:8960
	ds_read_b128 v[100:103], v117 offset:8960
	ds_read_b128 v[104:107], v118 offset:8960
	ds_read_b128 v[108:111], v119 offset:8960
	ds_read_b128 v[112:115], v120 offset:8960
	s_waitcnt lgkmcnt(9)
	v_mfma_f32_16x16x32_bf16 v[30:33], v[18:21], v[76:79], 0
	s_waitcnt lgkmcnt(8)
	v_mfma_f32_16x16x32_bf16 v[30:33], v[14:17], v[80:83], v[30:33]
	s_waitcnt lgkmcnt(7)
	v_mfma_f32_16x16x32_bf16 v[30:33], v[10:13], v[84:87], v[30:33]
	s_waitcnt lgkmcnt(6)
	v_mfma_f32_16x16x32_bf16 v[30:33], v[6:9], v[88:91], v[30:33]
	s_waitcnt lgkmcnt(5)
	v_mfma_f32_16x16x32_bf16 v[30:33], v[2:5], v[92:95], v[30:33]
	v_or_b32_e32 v121, 32, v46
	v_cndmask_b32_e32 v116, 0, v121, vcc
	v_xor_b32_e32 v116, v116, v45
	v_lshl_add_u32 v116, v116, 1, v47
	v_cndmask_b32_e64 v117, 0, v121, s[0:1]
	v_xor_b32_e32 v117, v117, v48
	v_lshl_add_u32 v117, v117, 1, v47
	v_cndmask_b32_e64 v118, 0, v121, s[38:39]
	v_xor_b32_e32 v118, v118, v49
	v_lshl_add_u32 v118, v118, 1, v47
	v_cndmask_b32_e64 v119, 0, v121, s[40:41]
	v_xor_b32_e32 v119, v119, v50
	v_lshl_add_u32 v119, v119, 1, v47
	v_cndmask_b32_e64 v120, 0, v121, s[42:43]
	v_xor_b32_e32 v120, v120, v52
	v_lshl_add_u32 v120, v120, 1, v47
	ds_read_b128 v[76:79], v116 offset:17920
	ds_read_b128 v[80:83], v117 offset:17920
	ds_read_b128 v[84:87], v118 offset:17920
	ds_read_b128 v[88:91], v119 offset:17920
	ds_read_b128 v[92:95], v120 offset:17920
	s_waitcnt lgkmcnt(9)
	v_mfma_f32_16x16x32_bf16 v[34:37], v[18:21], v[96:99], 0
	s_waitcnt lgkmcnt(8)
	v_mfma_f32_16x16x32_bf16 v[34:37], v[14:17], v[100:103], v[34:37]
	s_waitcnt lgkmcnt(7)
	v_mfma_f32_16x16x32_bf16 v[34:37], v[10:13], v[104:107], v[34:37]
	s_waitcnt lgkmcnt(6)
	v_mfma_f32_16x16x32_bf16 v[34:37], v[6:9], v[108:111], v[34:37]
	s_waitcnt lgkmcnt(5)
	v_mfma_f32_16x16x32_bf16 v[34:37], v[2:5], v[112:115], v[34:37]
	v_mul_f32_e32 v30, v39, v30
	v_mul_f32_e32 v31, v41, v31
	v_mul_f32_e32 v32, v42, v32
	v_mul_f32_e32 v33, v44, v33
	v_cvt_pk_bf16_f32 v122, v30, v31
	v_cvt_pk_bf16_f32 v123, v32, v33
	ds_write_b16 v53, v122
	ds_write_b16_d16_hi v40, v122
	ds_write_b16 v40, v123 offset:272
	ds_write_b16_d16_hi v40, v123 offset:544
	v_or_b32_e32 v121, 48, v46
	v_cndmask_b32_e32 v116, 0, v121, vcc
	v_xor_b32_e32 v116, v116, v45
	v_lshl_add_u32 v116, v116, 1, v47
	v_cndmask_b32_e64 v117, 0, v121, s[0:1]
	v_xor_b32_e32 v117, v117, v48
	v_lshl_add_u32 v117, v117, 1, v47
	v_cndmask_b32_e64 v118, 0, v121, s[38:39]
	v_xor_b32_e32 v118, v118, v49
	v_lshl_add_u32 v118, v118, 1, v47
	v_cndmask_b32_e64 v119, 0, v121, s[40:41]
	v_xor_b32_e32 v119, v119, v50
	v_lshl_add_u32 v119, v119, 1, v47
	v_cndmask_b32_e64 v120, 0, v121, s[42:43]
	v_xor_b32_e32 v120, v120, v52
	v_lshl_add_u32 v120, v120, 1, v47
	ds_read_b128 v[96:99], v116 offset:26880
	ds_read_b128 v[100:103], v117 offset:26880
	ds_read_b128 v[104:107], v118 offset:26880
	ds_read_b128 v[108:111], v119 offset:26880
	ds_read_b128 v[112:115], v120 offset:26880
	s_waitcnt lgkmcnt(13)
	v_mfma_f32_16x16x32_bf16 v[30:33], v[18:21], v[76:79], 0
	s_waitcnt lgkmcnt(12)
	v_mfma_f32_16x16x32_bf16 v[30:33], v[14:17], v[80:83], v[30:33]
	s_waitcnt lgkmcnt(11)
	v_mfma_f32_16x16x32_bf16 v[30:33], v[10:13], v[84:87], v[30:33]
	s_waitcnt lgkmcnt(10)
	v_mfma_f32_16x16x32_bf16 v[30:33], v[6:9], v[88:91], v[30:33]
	s_waitcnt lgkmcnt(9)
; __device__ void swa_item(const Params& p, int item) {
;     ...
;   _Pragma("unroll") for (int dt = 0; dt < 8; ++dt) {
;     f32x4 a = (f32x4){0.f, 0.f, 0.f, 0.f};
;     _Pragma("unroll") for (int kk = 0; kk < 5; ++kk) {
;       const int k0_ = w * 16 + kk * 32 + q * 8; const int ch_ = k0_ >> 3;
;       const int chp_ = (ch_ < 32) ? (ch_ ^ (((dt * 16 + c) >> 3) & 15)) : ch_;
;       bf16x8 vf = *(const bf16x8*)(Vt + (dt * 16 + c) * 280 + chp_ * 8);
;       a = __builtin_amdgcn_mfma_f32_16x16x32_bf16(pf[kk], vf, a, 0, 0, 0);
;     }
;     _Pragma("unroll") for (int jj = 0; jj < 4; ++jj) Ow[(q * 4 + jj) * 136 + dt * 16 + c] = f2bf(a[jj] * il[jj]);
;   }
	v_mfma_f32_16x16x32_bf16 v[30:33], v[2:5], v[92:95], v[30:33]
	v_mul_f32_e32 v34, v39, v34
	v_mul_f32_e32 v35, v41, v35
	v_mul_f32_e32 v36, v42, v36
	v_mul_f32_e32 v37, v44, v37
	v_cvt_pk_bf16_f32 v124, v34, v35
	v_cvt_pk_bf16_f32 v125, v36, v37
	ds_write_b16 v53, v124 offset:32
	ds_write_b16_d16_hi v40, v124 offset:32
	ds_write_b16 v40, v125 offset:304
	ds_write_b16_d16_hi v40, v125 offset:576
	v_or_b32_e32 v121, 64, v46
	v_cndmask_b32_e32 v116, 0, v121, vcc
	v_xor_b32_e32 v116, v116, v45
	v_lshl_add_u32 v116, v116, 1, v47
	v_cndmask_b32_e64 v117, 0, v121, s[0:1]
	v_xor_b32_e32 v117, v117, v48
	v_lshl_add_u32 v117, v117, 1, v47
	v_cndmask_b32_e64 v118, 0, v121, s[38:39]
	v_xor_b32_e32 v118, v118, v49
	v_lshl_add_u32 v118, v118, 1, v47
	v_cndmask_b32_e64 v119, 0, v121, s[40:41]
	v_xor_b32_e32 v119, v119, v50
	v_lshl_add_u32 v119, v119, 1, v47
	v_cndmask_b32_e64 v120, 0, v121, s[42:43]
	v_xor_b32_e32 v120, v120, v52
	v_lshl_add_u32 v120, v120, 1, v47
	ds_read_b128 v[76:79], v116 offset:35840
	ds_read_b128 v[80:83], v117 offset:35840
	ds_read_b128 v[84:87], v118 offset:35840
	ds_read_b128 v[88:91], v119 offset:35840
	ds_read_b128 v[92:95], v120 offset:35840
	s_waitcnt lgkmcnt(13)
	v_mfma_f32_16x16x32_bf16 v[34:37], v[18:21], v[96:99], 0
	s_waitcnt lgkmcnt(12)
	v_mfma_f32_16x16x32_bf16 v[34:37], v[14:17], v[100:103], v[34:37]
	s_waitcnt lgkmcnt(11)
	v_mfma_f32_16x16x32_bf16 v[34:37], v[10:13], v[104:107], v[34:37]
	s_waitcnt lgkmcnt(10)
	v_mfma_f32_16x16x32_bf16 v[34:37], v[6:9], v[108:111], v[34:37]
	s_waitcnt lgkmcnt(9)
	v_mfma_f32_16x16x32_bf16 v[34:37], v[2:5], v[112:115], v[34:37]
	v_mul_f32_e32 v30, v39, v30
	v_mul_f32_e32 v31, v41, v31
	v_mul_f32_e32 v32, v42, v32
	v_mul_f32_e32 v33, v44, v33
	v_cvt_pk_bf16_f32 v122, v30, v31
	v_cvt_pk_bf16_f32 v123, v32, v33
	ds_write_b16 v53, v122 offset:64
	ds_write_b16_d16_hi v40, v122 offset:64
	ds_write_b16 v40, v123 offset:336
	ds_write_b16_d16_hi v40, v123 offset:608
	v_or_b32_e32 v121, 0x50, v46
	v_cndmask_b32_e32 v116, 0, v121, vcc
	v_xor_b32_e32 v116, v116, v45
	v_lshl_add_u32 v116, v116, 1, v47
	v_cndmask_b32_e64 v117, 0, v121, s[0:1]
	v_xor_b32_e32 v117, v117, v48
	v_lshl_add_u32 v117, v117, 1, v47
	v_cndmask_b32_e64 v118, 0, v121, s[38:39]
	v_xor_b32_e32 v118, v118, v49
	v_lshl_add_u32 v118, v118, 1, v47
	v_cndmask_b32_e64 v119, 0, v121, s[40:41]
	v_xor_b32_e32 v119, v119, v50
	v_lshl_add_u32 v119, v119, 1, v47
	v_cndmask_b32_e64 v120, 0, v121, s[42:43]
	v_xor_b32_e32 v120, v120, v52
	v_lshl_add_u32 v120, v120, 1, v47
	ds_read_b128 v[96:99], v116 offset:44800
	ds_read_b128 v[100:103], v117 offset:44800
	ds_read_b128 v[104:107], v118 offset:44800
	ds_read_b128 v[108:111], v119 offset:44800
	ds_read_b128 v[112:115], v120 offset:44800
	s_waitcnt lgkmcnt(13)
	v_mfma_f32_16x16x32_bf16 v[30:33], v[18:21], v[76:79], 0
	s_waitcnt lgkmcnt(12)
	v_mfma_f32_16x16x32_bf16 v[30:33], v[14:17], v[80:83], v[30:33]
	s_waitcnt lgkmcnt(11)
	v_mfma_f32_16x16x32_bf16 v[30:33], v[10:13], v[84:87], v[30:33]
	s_waitcnt lgkmcnt(10)
	v_mfma_f32_16x16x32_bf16 v[30:33], v[6:9], v[88:91], v[30:33]
	s_waitcnt lgkmcnt(9)
	v_mfma_f32_16x16x32_bf16 v[30:33], v[2:5], v[92:95], v[30:33]
	v_mul_f32_e32 v34, v39, v34
	v_mul_f32_e32 v35, v41, v35
	v_mul_f32_e32 v36, v42, v36
	v_mul_f32_e32 v37, v44, v37
	v_cvt_pk_bf16_f32 v124, v34, v35
	v_cvt_pk_bf16_f32 v125, v36, v37
	ds_write_b16 v53, v124 offset:96
	ds_write_b16_d16_hi v40, v124 offset:96
	ds_write_b16 v40, v125 offset:368
	ds_write_b16_d16_hi v40, v125 offset:640
	v_or_b32_e32 v121, 0x60, v46
	v_cndmask_b32_e32 v116, 0, v121, vcc
	v_xor_b32_e32 v116, v116, v45
	v_lshl_add_u32 v116, v116, 1, v47
	v_cndmask_b32_e64 v117, 0, v121, s[0:1]
	v_xor_b32_e32 v117, v117, v48
	v_lshl_add_u32 v117, v117, 1, v47
	v_cndmask_b32_e64 v118, 0, v121, s[38:39]
	v_xor_b32_e32 v118, v118, v49
	v_lshl_add_u32 v118, v118, 1, v47
	v_cndmask_b32_e64 v119, 0, v121, s[40:41]
	v_xor_b32_e32 v119, v119, v50
	v_lshl_add_u32 v119, v119, 1, v47
	v_cndmask_b32_e64 v120, 0, v121, s[42:43]
	v_xor_b32_e32 v120, v120, v52
	v_lshl_add_u32 v120, v120, 1, v47
	ds_read_b128 v[76:79], v116 offset:53760
	ds_read_b128 v[80:83], v117 offset:53760
	ds_read_b128 v[84:87], v118 offset:53760
	ds_read_b128 v[88:91], v119 offset:53760
	ds_read_b128 v[92:95], v120 offset:53760
	s_waitcnt lgkmcnt(13)
	v_mfma_f32_16x16x32_bf16 v[34:37], v[18:21], v[96:99], 0
	s_waitcnt lgkmcnt(12)
	v_mfma_f32_16x16x32_bf16 v[34:37], v[14:17], v[100:103], v[34:37]
	s_waitcnt lgkmcnt(11)
	v_mfma_f32_16x16x32_bf16 v[34:37], v[10:13], v[104:107], v[34:37]
	s_waitcnt lgkmcnt(10)
	v_mfma_f32_16x16x32_bf16 v[34:37], v[6:9], v[108:111], v[34:37]
	s_waitcnt lgkmcnt(9)
	v_mfma_f32_16x16x32_bf16 v[34:37], v[2:5], v[112:115], v[34:37]
	v_mul_f32_e32 v30, v39, v30
	v_mul_f32_e32 v31, v41, v31
	v_mul_f32_e32 v32, v42, v32
	v_mul_f32_e32 v33, v44, v33
	v_cvt_pk_bf16_f32 v122, v30, v31
	v_cvt_pk_bf16_f32 v123, v32, v33
	ds_write_b16 v53, v122 offset:128
	ds_write_b16_d16_hi v40, v122 offset:128
	ds_write_b16 v40, v123 offset:400
	ds_write_b16_d16_hi v40, v123 offset:672
	v_or_b32_e32 v121, 0x70, v46
	v_cndmask_b32_e32 v116, 0, v121, vcc
	v_xor_b32_e32 v116, v116, v45
	v_lshl_add_u32 v116, v116, 1, v47
	v_cndmask_b32_e64 v117, 0, v121, s[0:1]
	v_xor_b32_e32 v117, v117, v48
	v_lshl_add_u32 v117, v117, 1, v47
	v_cndmask_b32_e64 v118, 0, v121, s[38:39]
	v_xor_b32_e32 v118, v118, v49
	v_lshl_add_u32 v118, v118, 1, v47
	v_cndmask_b32_e64 v119, 0, v121, s[40:41]
	v_xor_b32_e32 v119, v119, v50
	v_lshl_add_u32 v119, v119, 1, v47
	v_cndmask_b32_e64 v120, 0, v121, s[42:43]
	v_xor_b32_e32 v120, v120, v52
	v_lshl_add_u32 v120, v120, 1, v47
	ds_read_b128 v[96:99], v116 offset:62720
	ds_read_b128 v[100:103], v117 offset:62720
	ds_read_b128 v[104:107], v118 offset:62720
	ds_read_b128 v[108:111], v119 offset:62720
	ds_read_b128 v[112:115], v120 offset:62720
	s_waitcnt lgkmcnt(13)
; __device__ __forceinline__ float flog(float x) { return __builtin_amdgcn_logf(x) * 0.6931471805599453f; }
; __device__ void swa_item(const Params& p, int item) {
;     ...
;   _Pragma("unroll") for (int dt = 0; dt < 8; ++dt) {
;     f32x4 a = (f32x4){0.f, 0.f, 0.f, 0.f};
;     _Pragma("unroll") for (int kk = 0; kk < 5; ++kk) {
;       const int k0_ = w * 16 + kk * 32 + q * 8; const int ch_ = k0_ >> 3;
;       const int chp_ = (ch_ < 32) ? (ch_ ^ (((dt * 16 + c) >> 3) & 15)) : ch_;
;       bf16x8 vf = *(const bf16x8*)(Vt + (dt * 16 + c) * 280 + chp_ * 8);
;       a = __builtin_amdgcn_mfma_f32_16x16x32_bf16(pf[kk], vf, a, 0, 0, 0);
;     }
;     _Pragma("unroll") for (int jj = 0; jj < 4; ++jj) Ow[(q * 4 + jj) * 136 + dt * 16 + c] = f2bf(a[jj] * il[jj]);
;   }
;   asm volatile("s_waitcnt lgkmcnt(0)" ::: "memory");
;   _Pragma("unroll") for (int i = 0; i < 4; ++i) {
;     const int id = lane + 64 * i; const int rr = id >> 4, c8 = id & 15;
;     long orow = rowb + (long)(qb * 128 + w * 16 + rr) * dil + r;
;     *(bf16x8*)(buf + orow * 4608 + qcol + c8 * 8) = *(const bf16x8*)(Ow + rr * 136 + c8 * 8);
;   }
;   if (c == 0) {
;     _Pragma("unroll") for (int jj = 0; jj < 4; ++jj) {
;       long orow = rowb + (long)(qb * 128 + w * 16 + q * 4 + jj) * dil + r;
;       misc[MF_LSE + ((long)pat * MTOK + orow) * 4 + head] = mx[jj] + flog(ls[jj]);
;     }
;   }
	v_mfma_f32_16x16x32_bf16 v[30:33], v[18:21], v[76:79], 0
	s_waitcnt lgkmcnt(12)
	v_mfma_f32_16x16x32_bf16 v[30:33], v[14:17], v[80:83], v[30:33]
	s_waitcnt lgkmcnt(11)
	v_mfma_f32_16x16x32_bf16 v[30:33], v[10:13], v[84:87], v[30:33]
	s_waitcnt lgkmcnt(10)
	v_mfma_f32_16x16x32_bf16 v[30:33], v[6:9], v[88:91], v[30:33]
	s_waitcnt lgkmcnt(9)
	v_mfma_f32_16x16x32_bf16 v[30:33], v[2:5], v[92:95], v[30:33]
	v_mul_f32_e32 v34, v39, v34
	v_mul_f32_e32 v35, v41, v35
	v_mul_f32_e32 v36, v42, v36
	v_mul_f32_e32 v37, v44, v37
	v_cvt_pk_bf16_f32 v124, v34, v35
	v_cvt_pk_bf16_f32 v125, v36, v37
	ds_write_b16 v53, v124 offset:160
	ds_write_b16_d16_hi v40, v124 offset:160
	ds_write_b16 v40, v125 offset:432
	ds_write_b16_d16_hi v40, v125 offset:704
	v_cmp_eq_u32_e32 vcc, 0, v55
	s_waitcnt lgkmcnt(8)
	v_mfma_f32_16x16x32_bf16 v[34:37], v[18:21], v[96:99], 0
	s_waitcnt lgkmcnt(7)
	v_mfma_f32_16x16x32_bf16 v[34:37], v[14:17], v[100:103], v[34:37]
	s_waitcnt lgkmcnt(6)
	v_mfma_f32_16x16x32_bf16 v[34:37], v[10:13], v[104:107], v[34:37]
	s_waitcnt lgkmcnt(5)
	v_mfma_f32_16x16x32_bf16 v[34:37], v[6:9], v[108:111], v[34:37]
	s_waitcnt lgkmcnt(4)
	v_mfma_f32_16x16x32_bf16 v[34:37], v[2:5], v[112:115], v[34:37]
	v_mul_f32_e32 v30, v39, v30
	v_mul_f32_e32 v31, v41, v31
	v_mul_f32_e32 v32, v42, v32
	v_mul_f32_e32 v33, v44, v33
	v_cvt_pk_bf16_f32 v122, v30, v31
	v_cvt_pk_bf16_f32 v123, v32, v33
	ds_write_b16 v53, v122 offset:192
	ds_write_b16_d16_hi v40, v122 offset:192
	ds_write_b16 v40, v123 offset:464
	ds_write_b16_d16_hi v40, v123 offset:736
	v_or_b32_e32 v8, v51, v56
	v_ashrrev_i32_e32 v9, 31, v8
	s_nop 6
	v_mul_f32_e32 v34, v39, v34
	v_mul_f32_e32 v35, v41, v35
	v_mul_f32_e32 v36, v42, v36
	v_mul_f32_e32 v37, v44, v37
	v_cvt_pk_bf16_f32 v124, v34, v35
	v_cvt_pk_bf16_f32 v125, v36, v37
	ds_write_b16 v53, v124 offset:224
	ds_write_b16_d16_hi v40, v124 offset:224
	ds_write_b16 v40, v125 offset:496
	ds_write_b16_d16_hi v40, v125 offset:768
	v_lshlrev_b64 v[2:3], s22, v[8:9]
	v_lshl_add_u64 v[10:11], v[2:3], 0, s[26:27]
	v_mul_u32_u24_e32 v2, 0x110, v56
	s_waitcnt lgkmcnt(0)
	v_lshl_add_u64 v[6:7], s[52:53], 0, v[0:1]
	v_add3_u32 v0, v57, v0, v2
	ds_read_b128 v[2:5], v0
	v_mad_u64_u32 v[12:13], s[0:1], v10, s89, v[6:7]
	v_mad_i32_i24 v13, v11, s89, v13
	s_waitcnt lgkmcnt(0)
	global_store_dwordx4 v[12:13], v[2:5], off
	s_nop 1
	v_or_b32_e32 v2, 4, v8
	v_ashrrev_i32_e32 v3, 31, v2
	v_lshlrev_b64 v[2:3], s22, v[2:3]
	v_lshl_add_u64 v[10:11], v[2:3], 0, s[26:27]
	ds_read_b128 v[2:5], v0 offset:1088
	v_mad_u64_u32 v[12:13], s[0:1], v10, s89, v[6:7]
	v_mad_i32_i24 v13, v11, s89, v13
	s_waitcnt lgkmcnt(0)
	global_store_dwordx4 v[12:13], v[2:5], off
	s_nop 1
	v_or_b32_e32 v2, 8, v8
	v_ashrrev_i32_e32 v3, 31, v2
	v_lshlrev_b64 v[2:3], s22, v[2:3]
	v_lshl_add_u64 v[10:11], v[2:3], 0, s[26:27]
	ds_read_b128 v[2:5], v0 offset:2176
	v_mad_u64_u32 v[12:13], s[0:1], v10, s89, v[6:7]
	v_mad_i32_i24 v13, v11, s89, v13
	s_waitcnt lgkmcnt(0)
	global_store_dwordx4 v[12:13], v[2:5], off
	s_nop 1
	v_or_b32_e32 v2, 12, v8
	v_ashrrev_i32_e32 v3, 31, v2
	v_lshlrev_b64 v[2:3], s22, v[2:3]
	v_lshl_add_u64 v[8:9], v[2:3], 0, s[26:27]
	ds_read_b128 v[2:5], v0 offset:3264
	v_mad_u64_u32 v[6:7], s[0:1], v8, s89, v[6:7]
	v_mad_i32_i24 v7, v9, s89, v7
	s_waitcnt lgkmcnt(0)
	global_store_dwordx4 v[6:7], v[2:5], off
	s_and_saveexec_b64 s[0:1], vcc
	s_cbranch_execz .LBB0_101
	s_ashr_i32 s89, s88, 31
	s_lshl_b64 s[2:3], s[88:89], 19
	v_readlane_b32 s12, v252, 20
	v_log_f32_e32 v0, v26
	s_add_u32 s2, s12, s2
	v_readlane_b32 s12, v252, 21
	v_or_b32_e32 v2, v51, v38
	s_addc_u32 s3, s12, s3
	s_lshl_b32 s12, s23, 2
	s_add_u32 s2, s2, s12
	v_ashrrev_i32_e32 v3, 31, v2
	v_readlane_b32 s12, v254, 13
	v_lshlrev_b64 v[4:5], s22, v[2:3]
	v_readlane_b32 s13, v254, 14
	v_fmac_f32_e32 v22, 0x3f317218, v0
	v_log_f32_e32 v0, v27
	s_addc_u32 s3, s3, 0
	v_lshl_add_u64 v[4:5], v[4:5], 0, s[12:13]
	v_lshl_add_u64 v[4:5], v[4:5], 4, s[2:3]
	global_store_dword v[4:5], v22, off
	v_or_b32_e32 v4, 1, v2
	v_ashrrev_i32_e32 v5, 31, v4
	v_fmac_f32_e32 v23, 0x3f317218, v0
	v_log_f32_e32 v0, v28
	v_lshlrev_b64 v[4:5], s22, v[4:5]
	v_lshl_add_u64 v[4:5], v[4:5], 0, s[12:13]
	v_lshl_add_u64 v[4:5], v[4:5], 4, s[2:3]
	global_store_dword v[4:5], v23, off
	v_or_b32_e32 v4, 2, v2
	v_fmac_f32_e32 v24, 0x3f317218, v0
	v_or_b32_e32 v2, 3, v2
	v_log_f32_e32 v0, v29
	v_ashrrev_i32_e32 v5, 31, v4
	v_ashrrev_i32_e32 v3, 31, v2
	v_lshlrev_b64 v[4:5], s22, v[4:5]
	v_lshlrev_b64 v[2:3], s22, v[2:3]
	v_lshl_add_u64 v[4:5], v[4:5], 0, s[12:13]
	v_lshl_add_u64 v[2:3], v[2:3], 0, s[12:13]
	s_movk_i32 s89, 0x2400
	v_lshl_add_u64 v[4:5], v[4:5], 4, s[2:3]
	v_fmac_f32_e32 v25, 0x3f317218, v0
	v_lshl_add_u64 v[2:3], v[2:3], 4, s[2:3]
	global_store_dword v[4:5], v24, off
	global_store_dword v[2:3], v25, off
	s_branch .LBB0_101
